# phase-0 weight conversion: partial last round rotated onto the virtual blocks that have no modulation GEMV item
# baseline (speedup 1.0000x reference)
; DI void phase_prologue(const Params& p, char* smem) {
;     ...
;     for (int k = 0; k < (288 + G - 1) / G; ++k) { int it = bid + k * G; if (it >= 288) it = 287; mod_item(p, it, smem); }
;     for (int it = bid; it < 1536; it += G) rope_item(p, it);
;     for (int k = 0; k < (2 * 5184 + G - 1) / G; ++k) {
;         int it = bid + k * G; if (it >= 2 * 5184) it = 2 * 5184 - 1;
.LBB0_617:
	s_add_i32 s0, s7, 0x287f
	s_ashr_i32 s1, s0, 31
	s_abs_i32 s0, s0
	s_mul_hi_u32 s4, s0, s10
	s_mul_i32 s5, s4, s8
	s_sub_i32 s0, s0, s5
	s_xor_b32 s1, s1, s9
	s_add_i32 s5, s4, 1
	s_sub_i32 s6, s0, s8
	s_cmp_ge_u32 s0, s8
	s_cselect_b32 s4, s5, s4
	s_cselect_b32 s0, s6, s0
	s_add_i32 s5, s4, 1
	s_cmp_ge_u32 s0, s8
	s_cselect_b32 s0, s5, s4
	s_xor_b32 s0, s0, s1
	s_sub_i32 s17, s0, s1
	s_cmp_lt_i32 s17, 1
	s_cbranch_scc1 .LBB0_665
	v_readlane_b32 s56, v253, 6
	v_readlane_b32 s47, v253, 4
	v_readlane_b32 s57, v253, 7
	v_readlane_b32 s58, v253, 8
	v_readlane_b32 s59, v253, 9
	v_readlane_b32 s60, v253, 10
	v_readlane_b32 s61, v253, 11
	v_readlane_b32 s62, v253, 12
	v_readlane_b32 s63, v253, 13
	v_readlane_b32 s64, v253, 14
	v_readlane_b32 s65, v253, 15
	v_readlane_b32 s66, v253, 16
	v_readlane_b32 s67, v253, 17
	v_readlane_b32 s68, v253, 18
	v_readlane_b32 s69, v253, 19
	v_readlane_b32 s70, v253, 20
	v_readlane_b32 s71, v253, 21
	s_addk_i32 s16, 0xe0
	s_cmp_ge_i32 s16, s47
	s_cselect_b32 s0, s47, 0
	s_sub_i32 s16, s16, s0
	s_branch .LBB0_630
